# sample_gemm: four chunk loads in flight (four register sets), counted vmcnt waits
# baseline (speedup 1.0000x reference)
.LBB0_683:
	v_readfirstlane_b32 s98, v38
	v_readfirstlane_b32 s99, v39
	v_readlane_b32 vcc_lo, v252, 60
	s_lshr_b32 vcc_lo, vcc_lo, 3
	s_and_b32 s40, vcc_lo, 1
	s_lshl_b32 s41, s36, 4
	s_mul_i32 s40, s40, s41
	s_sub_u32 s98, s98, s40
	s_subb_u32 s99, s99, 0
	v_lshl_add_u32 v106, vcc_lo, 6, v162
	v_lshrrev_b32_e32 v107, 5, v106
	v_and_b32_e32 v108, 31, v106
	v_lshlrev_b32_e32 v108, 4, v108
	v_mov_b32_e32 v109, 0
	v_mov_b64_e32 v[112:113], s[98:99]
	v_lshl_add_u64 v[112:113], v[112:113], 0, v[108:109]
	v_mad_u64_u32 v[110:111], s[40:41], s36, v107, v[112:113]
	v_readfirstlane_b32 s98, v40
	v_readfirstlane_b32 s99, v41
	s_lshr_b32 s40, vcc_lo, 1
	s_lshl_b32 s41, s20, 4
	s_mul_i32 s40, s40, s41
	s_add_u32 s40, s40, 0x100
	s_sub_u32 s98, s98, s40
	s_subb_u32 s99, s99, 0
	v_mov_b64_e32 v[112:113], s[98:99]
	v_lshl_add_u64 v[112:113], v[112:113], 0, v[108:109]
	v_mad_u64_u32 v[114:115], s[40:41], s20, v107, v[112:113]
	s_lshl_b32 s40, s36, 4
	s_mov_b32 s41, 0
	v_lshl_add_u64 v[116:117], v[110:111], 0, s[40:41]
	s_lshl_b32 s40, s20, 4
	v_lshl_add_u64 v[118:119], v[114:115], 0, s[40:41]
	v_lshl_add_u64 v[120:121], v[118:119], 0, s[40:41]
	v_lshl_add_u64 v[122:123], v[120:121], 0, s[40:41]
	v_mul_u32_u24_e32 v136, 0x210, v107
	v_add_u32_e32 v136, v136, v108
	v_and_b32_e32 v143, 15, v162
	v_lshrrev_b32_e32 v160, 4, v162
	s_and_b32 s40, vcc_lo, 1
	s_lshl_b32 s40, s40, 4
	v_add_u32_e32 v137, s40, v143
	v_mul_u32_u24_e32 v137, 0x210, v137
	v_lshl_add_u32 v137, v160, 4, v137
	s_lshr_b32 s40, vcc_lo, 1
	s_lshl_b32 s40, s40, 4
	v_add_u32_e32 v142, s40, v143
	v_mul_u32_u24_e32 v142, 0x210, v142
	v_lshl_add_u32 v142, v160, 4, v142
	v_add_u32_e32 v142, 0x4200, v142
	global_load_dwordx4 v[82:85], v[110:111], off
	global_load_dwordx4 v[86:89], v[116:117], off
	global_load_dwordx4 v[90:93], v[114:115], off
	global_load_dwordx4 v[94:97], v[118:119], off
	global_load_dwordx4 v[98:101], v[120:121], off
	global_load_dwordx4 v[102:105], v[122:123], off
	v_lshl_add_u64 v[110:111], v[110:111], 0, s[50:51]
	v_lshl_add_u64 v[116:117], v[116:117], 0, s[50:51]
	v_lshl_add_u64 v[114:115], v[114:115], 0, s[50:51]
	v_lshl_add_u64 v[118:119], v[118:119], 0, s[50:51]
	v_lshl_add_u64 v[120:121], v[120:121], 0, s[50:51]
	v_lshl_add_u64 v[122:123], v[122:123], 0, s[50:51]
	s_mov_b32 s41, 1
	s_movk_i32 s98, 0x100
	s_cmp_ge_u32 s98, s22
	s_cbranch_scc1 .Lsg_pro_done
	global_load_dwordx4 v[182:185], v[110:111], off
	global_load_dwordx4 v[186:189], v[116:117], off
	global_load_dwordx4 v[190:193], v[114:115], off
	global_load_dwordx4 v[194:197], v[118:119], off
	global_load_dwordx4 v[198:201], v[120:121], off
	global_load_dwordx4 v[202:205], v[122:123], off
	v_lshl_add_u64 v[110:111], v[110:111], 0, s[50:51]
	v_lshl_add_u64 v[116:117], v[116:117], 0, s[50:51]
	v_lshl_add_u64 v[114:115], v[114:115], 0, s[50:51]
	v_lshl_add_u64 v[118:119], v[118:119], 0, s[50:51]
	v_lshl_add_u64 v[120:121], v[120:121], 0, s[50:51]
	v_lshl_add_u64 v[122:123], v[122:123], 0, s[50:51]
	s_add_u32 s41, s41, 1
	s_addk_i32 s98, 0x100
	s_cmp_ge_u32 s98, s22
	s_cbranch_scc1 .Lsg_pro_done
	global_load_dwordx4 v[206:209], v[110:111], off
	global_load_dwordx4 v[210:213], v[116:117], off
	global_load_dwordx4 v[214:217], v[114:115], off
	global_load_dwordx4 v[218:221], v[118:119], off
	global_load_dwordx4 v[222:225], v[120:121], off
	global_load_dwordx4 v[226:229], v[122:123], off
	v_lshl_add_u64 v[110:111], v[110:111], 0, s[50:51]
	v_lshl_add_u64 v[116:117], v[116:117], 0, s[50:51]
	v_lshl_add_u64 v[114:115], v[114:115], 0, s[50:51]
	v_lshl_add_u64 v[118:119], v[118:119], 0, s[50:51]
	v_lshl_add_u64 v[120:121], v[120:121], 0, s[50:51]
	v_lshl_add_u64 v[122:123], v[122:123], 0, s[50:51]
	s_add_u32 s41, s41, 1
	s_addk_i32 s98, 0x100
	s_cmp_ge_u32 s98, s22
	s_cbranch_scc1 .Lsg_pro_done
	global_load_dwordx4 v[230:233], v[110:111], off
	global_load_dwordx4 v[234:237], v[116:117], off
	global_load_dwordx4 v[238:241], v[114:115], off
	global_load_dwordx4 v[242:245], v[118:119], off
	global_load_dwordx4 v[246:249], v[120:121], off
	global_load_dwordx4 v[124:127], v[122:123], off
	v_lshl_add_u64 v[110:111], v[110:111], 0, s[50:51]
	v_lshl_add_u64 v[116:117], v[116:117], 0, s[50:51]
	v_lshl_add_u64 v[114:115], v[114:115], 0, s[50:51]
	v_lshl_add_u64 v[118:119], v[118:119], 0, s[50:51]
	v_lshl_add_u64 v[120:121], v[120:121], 0, s[50:51]
	v_lshl_add_u64 v[122:123], v[122:123], 0, s[50:51]
	s_add_u32 s41, s41, 1
	s_addk_i32 s98, 0x100
.Lsg_pro_done:
	s_mov_b32 s40, 0
.Lsg_loop:
.Lsg_step0:
	v_add_u32_e32 v161, s40, v136
	s_cmp_ge_u32 s41, 4
	s_cbranch_scc1 .Lsg_w18_0
	s_cmp_eq_u32 s41, 3
	s_cbranch_scc1 .Lsg_w12_0
	s_cmp_eq_u32 s41, 2
	s_cbranch_scc1 .Lsg_w6_0
	s_waitcnt vmcnt(0)
	s_branch .Lsg_go_0
.Lsg_w18_0:
	s_waitcnt vmcnt(18)
	s_branch .Lsg_go_0
.Lsg_w12_0:
	s_waitcnt vmcnt(12)
	s_branch .Lsg_go_0
.Lsg_w6_0:
	s_waitcnt vmcnt(6)
.Lsg_go_0:
	ds_write_b128 v161, v[82:85]
	ds_write_b128 v161, v[86:89] offset:8448
	ds_write_b128 v161, v[90:93] offset:16896
	ds_write_b128 v161, v[94:97] offset:25344
	ds_write_b128 v161, v[98:101] offset:33792
	ds_write_b128 v161, v[102:105] offset:42240
	s_addk_i32 s39, 0x100
	s_cmp_ge_u32 s98, s22
	s_cbranch_scc1 .Lsg_norefill_0
	global_load_dwordx4 v[82:85], v[110:111], off
	global_load_dwordx4 v[86:89], v[116:117], off
	global_load_dwordx4 v[90:93], v[114:115], off
	global_load_dwordx4 v[94:97], v[118:119], off
	global_load_dwordx4 v[98:101], v[120:121], off
	global_load_dwordx4 v[102:105], v[122:123], off
	v_lshl_add_u64 v[110:111], v[110:111], 0, s[50:51]
	v_lshl_add_u64 v[116:117], v[116:117], 0, s[50:51]
	v_lshl_add_u64 v[114:115], v[114:115], 0, s[50:51]
	v_lshl_add_u64 v[118:119], v[118:119], 0, s[50:51]
	v_lshl_add_u64 v[120:121], v[120:121], 0, s[50:51]
	v_lshl_add_u64 v[122:123], v[122:123], 0, s[50:51]
	s_addk_i32 s98, 0x100
	s_branch .Lsg_refilled_0
.Lsg_norefill_0:
	s_sub_u32 s41, s41, 1
.Lsg_refilled_0:
	v_add_u32_e32 v143, s40, v137
	v_add_u32_e32 v160, s40, v142
	s_waitcnt lgkmcnt(0)
	s_barrier
	ds_read_b128 v[46:49], v143
	ds_read_b128 v[54:57], v160
	ds_read_b128 v[50:53], v143 offset:64
	ds_read_b128 v[58:61], v160 offset:64
	ds_read_b128 v[62:65], v143 offset:128
	ds_read_b128 v[66:69], v160 offset:128
	ds_read_b128 v[70:73], v143 offset:192
	ds_read_b128 v[74:77], v160 offset:192
	ds_read_b128 v[132:135], v143 offset:256
	ds_read_b128 v[148:151], v160 offset:256
	ds_read_b128 v[144:147], v143 offset:320
	ds_read_b128 v[152:155], v160 offset:320
	ds_read_b128 v[106:109], v143 offset:384
	ds_read_b128 v[156:159], v160 offset:384
	ds_read_b128 v[38:41], v143 offset:448
	ds_read_b128 v[78:81], v160 offset:448
	s_waitcnt lgkmcnt(14)
	v_mfma_f32_16x16x32_bf16 v[2:5], v[46:49], v[54:57], v[2:5]
	s_waitcnt lgkmcnt(12)
	v_mfma_f32_16x16x32_bf16 v[2:5], v[50:53], v[58:61], v[2:5]
	s_waitcnt lgkmcnt(10)
	v_mfma_f32_16x16x32_bf16 v[2:5], v[62:65], v[66:69], v[2:5]
	s_waitcnt lgkmcnt(8)
	v_mfma_f32_16x16x32_bf16 v[2:5], v[70:73], v[74:77], v[2:5]
	s_waitcnt lgkmcnt(6)
	v_mfma_f32_16x16x32_bf16 v[2:5], v[132:135], v[148:151], v[2:5]
	s_waitcnt lgkmcnt(4)
	v_mfma_f32_16x16x32_bf16 v[2:5], v[144:147], v[152:155], v[2:5]
	s_waitcnt lgkmcnt(2)
	v_mfma_f32_16x16x32_bf16 v[2:5], v[106:109], v[156:159], v[2:5]
	s_waitcnt lgkmcnt(0)
	v_mfma_f32_16x16x32_bf16 v[2:5], v[38:41], v[78:81], v[2:5]
	s_xor_b32 s40, s40, 0xc600
	s_cmp_ge_u32 s39, s22
	s_cbranch_scc1 .Lsg_exit
.Lsg_step1:
	v_add_u32_e32 v161, s40, v136
	s_cmp_ge_u32 s41, 4
	s_cbranch_scc1 .Lsg_w18_1
	s_cmp_eq_u32 s41, 3
	s_cbranch_scc1 .Lsg_w12_1
	s_cmp_eq_u32 s41, 2
	s_cbranch_scc1 .Lsg_w6_1
	s_waitcnt vmcnt(0)
	s_branch .Lsg_go_1

.Lsg_go_1:
	ds_write_b128 v161, v[182:185]
	ds_write_b128 v161, v[186:189] offset:8448
	ds_write_b128 v161, v[190:193] offset:16896
	ds_write_b128 v161, v[194:197] offset:25344
	ds_write_b128 v161, v[198:201] offset:33792
	ds_write_b128 v161, v[202:205] offset:42240
	s_addk_i32 s39, 0x100
	s_cmp_ge_u32 s98, s22
	s_cbranch_scc1 .Lsg_norefill_1
	global_load_dwordx4 v[182:185], v[110:111], off
	global_load_dwordx4 v[186:189], v[116:117], off
	global_load_dwordx4 v[190:193], v[114:115], off
	global_load_dwordx4 v[194:197], v[118:119], off
	global_load_dwordx4 v[198:201], v[120:121], off
	global_load_dwordx4 v[202:205], v[122:123], off
	v_lshl_add_u64 v[110:111], v[110:111], 0, s[50:51]
	v_lshl_add_u64 v[116:117], v[116:117], 0, s[50:51]
	v_lshl_add_u64 v[114:115], v[114:115], 0, s[50:51]
	v_lshl_add_u64 v[118:119], v[118:119], 0, s[50:51]
	v_lshl_add_u64 v[120:121], v[120:121], 0, s[50:51]
	v_lshl_add_u64 v[122:123], v[122:123], 0, s[50:51]
	s_addk_i32 s98, 0x100
	s_branch .Lsg_refilled_1

.Lsg_go_2:
	ds_write_b128 v161, v[206:209]
	ds_write_b128 v161, v[210:213] offset:8448
	ds_write_b128 v161, v[214:217] offset:16896
	ds_write_b128 v161, v[218:221] offset:25344
	ds_write_b128 v161, v[222:225] offset:33792
	ds_write_b128 v161, v[226:229] offset:42240
	s_addk_i32 s39, 0x100
	s_cmp_ge_u32 s98, s22
	s_cbranch_scc1 .Lsg_norefill_2
	global_load_dwordx4 v[206:209], v[110:111], off
	global_load_dwordx4 v[210:213], v[116:117], off
	global_load_dwordx4 v[214:217], v[114:115], off
	global_load_dwordx4 v[218:221], v[118:119], off
	global_load_dwordx4 v[222:225], v[120:121], off
	global_load_dwordx4 v[226:229], v[122:123], off
	v_lshl_add_u64 v[110:111], v[110:111], 0, s[50:51]
	v_lshl_add_u64 v[116:117], v[116:117], 0, s[50:51]
	v_lshl_add_u64 v[114:115], v[114:115], 0, s[50:51]
	v_lshl_add_u64 v[118:119], v[118:119], 0, s[50:51]
	v_lshl_add_u64 v[120:121], v[120:121], 0, s[50:51]
	v_lshl_add_u64 v[122:123], v[122:123], 0, s[50:51]
	s_addk_i32 s98, 0x100
	s_branch .Lsg_refilled_2

.Lsg_go_3:
	ds_write_b128 v161, v[230:233]
	ds_write_b128 v161, v[234:237] offset:8448
	ds_write_b128 v161, v[238:241] offset:16896
	ds_write_b128 v161, v[242:245] offset:25344
	ds_write_b128 v161, v[246:249] offset:33792
	ds_write_b128 v161, v[124:127] offset:42240
	s_addk_i32 s39, 0x100
	s_cmp_ge_u32 s98, s22
	s_cbranch_scc1 .Lsg_norefill_3
	global_load_dwordx4 v[230:233], v[110:111], off
	global_load_dwordx4 v[234:237], v[116:117], off
	global_load_dwordx4 v[238:241], v[114:115], off
	global_load_dwordx4 v[242:245], v[118:119], off
	global_load_dwordx4 v[246:249], v[120:121], off
	global_load_dwordx4 v[124:127], v[122:123], off
	v_lshl_add_u64 v[110:111], v[110:111], 0, s[50:51]
	v_lshl_add_u64 v[116:117], v[116:117], 0, s[50:51]
	v_lshl_add_u64 v[114:115], v[114:115], 0, s[50:51]
	v_lshl_add_u64 v[118:119], v[118:119], 0, s[50:51]
	v_lshl_add_u64 v[120:121], v[120:121], 0, s[50:51]
	v_lshl_add_u64 v[122:123], v[122:123], 0, s[50:51]
	s_addk_i32 s98, 0x100
	s_branch .Lsg_refilled_3

.Lsg_refilled_3:
	v_add_u32_e32 v143, s40, v137
	v_add_u32_e32 v160, s40, v142
	s_waitcnt lgkmcnt(0)
	s_barrier
	ds_read_b128 v[46:49], v143
	ds_read_b128 v[54:57], v160
	ds_read_b128 v[50:53], v143 offset:64
	ds_read_b128 v[58:61], v160 offset:64
	ds_read_b128 v[62:65], v143 offset:128
	ds_read_b128 v[66:69], v160 offset:128
	ds_read_b128 v[70:73], v143 offset:192
	ds_read_b128 v[74:77], v160 offset:192
	ds_read_b128 v[132:135], v143 offset:256
	ds_read_b128 v[148:151], v160 offset:256
	ds_read_b128 v[144:147], v143 offset:320
	ds_read_b128 v[152:155], v160 offset:320
	ds_read_b128 v[106:109], v143 offset:384
	ds_read_b128 v[156:159], v160 offset:384
	ds_read_b128 v[38:41], v143 offset:448
	ds_read_b128 v[78:81], v160 offset:448
	s_waitcnt lgkmcnt(14)
	v_mfma_f32_16x16x32_bf16 v[2:5], v[46:49], v[54:57], v[2:5]
	s_waitcnt lgkmcnt(12)
	v_mfma_f32_16x16x32_bf16 v[2:5], v[50:53], v[58:61], v[2:5]
	s_waitcnt lgkmcnt(10)
	v_mfma_f32_16x16x32_bf16 v[2:5], v[62:65], v[66:69], v[2:5]
	s_waitcnt lgkmcnt(8)
	v_mfma_f32_16x16x32_bf16 v[2:5], v[70:73], v[74:77], v[2:5]
	s_waitcnt lgkmcnt(6)
	v_mfma_f32_16x16x32_bf16 v[2:5], v[132:135], v[148:151], v[2:5]
	s_waitcnt lgkmcnt(4)
	v_mfma_f32_16x16x32_bf16 v[2:5], v[144:147], v[152:155], v[2:5]
	s_waitcnt lgkmcnt(2)
	v_mfma_f32_16x16x32_bf16 v[2:5], v[106:109], v[156:159], v[2:5]
	s_waitcnt lgkmcnt(0)
	v_mfma_f32_16x16x32_bf16 v[2:5], v[38:41], v[78:81], v[2:5]
	s_xor_b32 s40, s40, 0xc600
	s_cmp_ge_u32 s39, s22
	s_cbranch_scc0 .Lsg_loop
.Lsg_exit:
	s_barrier
	s_andn2_b64 vcc, exec, s[18:19]
	s_cbranch_vccnz .LBB0_686
	s_lshl_b32 s72, s5, 11
	v_lshl_add_u64 v[38:39], v[24:25], 0, s[72:73]
	v_lshl_add_u64 v[40:41], v[38:39], 0, v[26:27]
	v_lshl_add_u64 v[46:47], v[38:39], 0, v[28:29]
	global_load_ushort v40, v[40:41], off
	s_nop 0
	global_load_ushort v41, v[46:47], off
	s_waitcnt vmcnt(1)
	v_lshlrev_b32_e32 v40, 16, v40
	s_waitcnt vmcnt(0)
	v_lshlrev_b32_e32 v41, 16, v41
	v_pk_fma_f32 v[2:3], v[2:3], v[40:41], v[36:37]
	v_lshl_add_u64 v[36:37], v[38:39], 0, v[30:31]
	v_lshl_add_u64 v[38:39], v[38:39], 0, v[32:33]
	global_load_ushort v36, v[36:37], off
	s_nop 0
	global_load_ushort v37, v[38:39], off
	s_waitcnt vmcnt(1)
	v_lshlrev_b32_e32 v36, 16, v36
	s_waitcnt vmcnt(0)
	v_lshlrev_b32_e32 v37, 16, v37
	v_pk_fma_f32 v[4:5], v[4:5], v[36:37], v[34:35]
